# K-loops P1/P4: all per-segment s_setprio toggles removed (equal priority, age arbitration)
# speedup vs baseline: 1.0093x; 1.0020x over previous
.LBB0_165:
	ds_read_b128 v[114:117], v177
	ds_read_b128 v[118:121], v177 offset:1024
	ds_read_b128 v[122:125], v177 offset:2048
	ds_read_b128 v[126:129], v177 offset:3072
	ds_read_b128 v[182:185], v178
	ds_read_b128 v[186:189], v178 offset:1024
	ds_read_b128 v[190:193], v178 offset:2048
	ds_read_b128 v[194:197], v178 offset:3072
	s_add_u32 s0, s70, 0xfff80080
	s_addc_u32 s1, s71, -1
	s_cmp_eq_u32 s76, 28
	s_cselect_b32 s13, s9, s1
	s_cselect_b32 s12, s61, s0
	s_cselect_b32 s1, s63, s21
	s_cselect_b32 s0, s75, s20
	v_lshl_add_u64 v[174:175], s[70:71], 0, v[166:167]
	s_add_i32 m0, s35, 0xc000
	ds_read_b128 v[198:201], v179
	ds_read_b128 v[202:205], v179 offset:1024
	ds_read_b128 v[206:209], v179 offset:2048
	ds_read_b128 v[210:213], v179 offset:3072
	ds_read_b128 v[214:217], v179 offset:4096
	ds_read_b128 v[218:221], v179 offset:5120
	ds_read_b128 v[222:225], v179 offset:6144
	ds_read_b128 v[226:229], v179 offset:7168
	global_load_lds_dwordx4 v[174:175], off
	v_lshl_add_u64 v[174:175], s[70:71], 0, v[168:169]
	s_add_i32 m0, s35, 0xe000
	s_nop 0
	global_load_lds_dwordx4 v[174:175], off
	s_waitcnt vmcnt(8)
	s_waitcnt lgkmcnt(0)
	s_barrier
	s_waitcnt lgkmcnt(0)
	v_mfma_f32_16x16x32_bf16 v[142:145], v[114:117], v[198:201], v[142:145]
	v_mfma_f32_16x16x32_bf16 v[138:141], v[122:125], v[198:201], v[138:141]
	v_mfma_f32_16x16x32_bf16 v[110:113], v[114:117], v[206:209], v[110:113]
	v_mfma_f32_16x16x32_bf16 v[106:109], v[122:125], v[206:209], v[106:109]
	v_mfma_f32_16x16x32_bf16 v[94:97], v[114:117], v[214:217], v[94:97]
	v_mfma_f32_16x16x32_bf16 v[90:93], v[122:125], v[214:217], v[90:93]
	v_mfma_f32_16x16x32_bf16 v[78:81], v[114:117], v[222:225], v[78:81]
	v_mfma_f32_16x16x32_bf16 v[74:77], v[122:125], v[222:225], v[74:77]
	v_mfma_f32_16x16x32_bf16 v[142:145], v[118:121], v[202:205], v[142:145]
	v_mfma_f32_16x16x32_bf16 v[138:141], v[126:129], v[202:205], v[138:141]
	v_mfma_f32_16x16x32_bf16 v[110:113], v[118:121], v[210:213], v[110:113]
	v_mfma_f32_16x16x32_bf16 v[106:109], v[126:129], v[210:213], v[106:109]
	v_mfma_f32_16x16x32_bf16 v[94:97], v[118:121], v[218:221], v[94:97]
	v_mfma_f32_16x16x32_bf16 v[90:93], v[126:129], v[218:221], v[90:93]
	v_mfma_f32_16x16x32_bf16 v[78:81], v[118:121], v[226:229], v[78:81]
	v_mfma_f32_16x16x32_bf16 v[74:77], v[126:129], v[226:229], v[74:77]
	v_mfma_f32_16x16x32_bf16 v[134:137], v[182:185], v[198:201], v[134:137]
	v_mfma_f32_16x16x32_bf16 v[130:133], v[190:193], v[198:201], v[130:133]
	v_mfma_f32_16x16x32_bf16 v[102:105], v[182:185], v[206:209], v[102:105]
	v_mfma_f32_16x16x32_bf16 v[98:101], v[190:193], v[206:209], v[98:101]
	v_mfma_f32_16x16x32_bf16 v[86:89], v[182:185], v[214:217], v[86:89]
	v_mfma_f32_16x16x32_bf16 v[82:85], v[190:193], v[214:217], v[82:85]
	v_mfma_f32_16x16x32_bf16 v[70:73], v[182:185], v[222:225], v[70:73]
	v_mfma_f32_16x16x32_bf16 v[66:69], v[190:193], v[222:225], v[66:69]
	v_mfma_f32_16x16x32_bf16 v[134:137], v[186:189], v[202:205], v[134:137]
	v_mfma_f32_16x16x32_bf16 v[130:133], v[194:197], v[202:205], v[130:133]
	v_mfma_f32_16x16x32_bf16 v[102:105], v[186:189], v[210:213], v[102:105]
	v_mfma_f32_16x16x32_bf16 v[98:101], v[194:197], v[210:213], v[98:101]
	v_mfma_f32_16x16x32_bf16 v[86:89], v[186:189], v[218:221], v[86:89]
	v_mfma_f32_16x16x32_bf16 v[82:85], v[194:197], v[218:221], v[82:85]
	v_mfma_f32_16x16x32_bf16 v[70:73], v[186:189], v[226:229], v[70:73]
	v_mfma_f32_16x16x32_bf16 v[66:69], v[194:197], v[226:229], v[66:69]
	s_barrier
	s_add_i32 s77, s72, s34
	v_lshl_add_u64 v[174:175], s[0:1], 0, v[148:149]
	s_mov_b32 m0, s77
	ds_read_b128 v[198:201], v179 offset:16384
	ds_read_b128 v[202:205], v179 offset:17408
	ds_read_b128 v[206:209], v179 offset:18432
	ds_read_b128 v[210:213], v179 offset:19456
	ds_read_b128 v[214:217], v179 offset:20480
	ds_read_b128 v[218:221], v179 offset:21504
	ds_read_b128 v[222:225], v179 offset:22528
	ds_read_b128 v[226:229], v179 offset:23552
	global_load_lds_dwordx4 v[174:175], off
	s_add_i32 m0, s77, 0x2000
	s_add_u32 s78, s0, 0x20000
	v_lshl_add_u64 v[230:231], s[0:1], 0, v[152:153]
	s_addc_u32 s79, s1, 0
	s_add_i32 s77, s73, s34
	global_load_lds_dwordx4 v[230:231], off
	v_lshl_add_u64 v[232:233], s[78:79], 0, v[148:149]
	s_mov_b32 m0, s77
	v_lshl_add_u64 v[234:235], s[12:13], 0, v[150:151]
	global_load_lds_dwordx4 v[232:233], off
	v_lshl_add_u64 v[232:233], s[78:79], 0, v[152:153]
	s_add_i32 m0, s77, 0x2000
	s_nop 0
	global_load_lds_dwordx4 v[232:233], off
	v_lshl_add_u64 v[232:233], s[12:13], 0, v[146:147]
	s_mov_b32 m0, s35
	s_nop 0
	global_load_lds_dwordx4 v[232:233], off
	s_mov_b32 m0, s36
	s_nop 0
	global_load_lds_dwordx4 v[234:235], off
	s_waitcnt vmcnt(8)
	s_waitcnt lgkmcnt(0)
	s_barrier
	s_waitcnt lgkmcnt(0)
	v_mfma_f32_16x16x32_bf16 v[62:65], v[114:117], v[198:201], v[62:65]
	v_mfma_f32_16x16x32_bf16 v[58:61], v[122:125], v[198:201], v[58:61]
	v_mfma_f32_16x16x32_bf16 v[46:49], v[114:117], v[206:209], v[46:49]
	v_mfma_f32_16x16x32_bf16 v[42:45], v[122:125], v[206:209], v[42:45]
	v_mfma_f32_16x16x32_bf16 v[30:33], v[114:117], v[214:217], v[30:33]
	v_mfma_f32_16x16x32_bf16 v[26:29], v[122:125], v[214:217], v[26:29]
	v_mfma_f32_16x16x32_bf16 v[14:17], v[114:117], v[222:225], v[14:17]
	v_mfma_f32_16x16x32_bf16 v[10:13], v[122:125], v[222:225], v[10:13]
	v_mfma_f32_16x16x32_bf16 v[62:65], v[118:121], v[202:205], v[62:65]
	v_mfma_f32_16x16x32_bf16 v[58:61], v[126:129], v[202:205], v[58:61]
	v_mfma_f32_16x16x32_bf16 v[46:49], v[118:121], v[210:213], v[46:49]
	v_mfma_f32_16x16x32_bf16 v[42:45], v[126:129], v[210:213], v[42:45]
	v_mfma_f32_16x16x32_bf16 v[30:33], v[118:121], v[218:221], v[30:33]
	v_mfma_f32_16x16x32_bf16 v[26:29], v[126:129], v[218:221], v[26:29]
	v_mfma_f32_16x16x32_bf16 v[14:17], v[118:121], v[226:229], v[14:17]
	v_mfma_f32_16x16x32_bf16 v[10:13], v[126:129], v[226:229], v[10:13]
	v_mfma_f32_16x16x32_bf16 v[54:57], v[182:185], v[198:201], v[54:57]
	v_mfma_f32_16x16x32_bf16 v[50:53], v[190:193], v[198:201], v[50:53]
	v_mfma_f32_16x16x32_bf16 v[38:41], v[182:185], v[206:209], v[38:41]
	v_mfma_f32_16x16x32_bf16 v[34:37], v[190:193], v[206:209], v[34:37]
	v_mfma_f32_16x16x32_bf16 v[22:25], v[182:185], v[214:217], v[22:25]
	v_mfma_f32_16x16x32_bf16 v[18:21], v[190:193], v[214:217], v[18:21]
	v_mfma_f32_16x16x32_bf16 v[6:9], v[182:185], v[222:225], v[6:9]
	v_mfma_f32_16x16x32_bf16 v[2:5], v[190:193], v[222:225], v[2:5]
	v_mfma_f32_16x16x32_bf16 v[54:57], v[186:189], v[202:205], v[54:57]
	v_mfma_f32_16x16x32_bf16 v[50:53], v[194:197], v[202:205], v[50:53]
	v_mfma_f32_16x16x32_bf16 v[38:41], v[186:189], v[210:213], v[38:41]
	v_mfma_f32_16x16x32_bf16 v[34:37], v[194:197], v[210:213], v[34:37]
	v_mfma_f32_16x16x32_bf16 v[22:25], v[186:189], v[218:221], v[22:25]
	v_mfma_f32_16x16x32_bf16 v[18:21], v[194:197], v[218:221], v[18:21]
	v_mfma_f32_16x16x32_bf16 v[6:9], v[186:189], v[226:229], v[6:9]
	v_mfma_f32_16x16x32_bf16 v[2:5], v[194:197], v[226:229], v[2:5]
	s_barrier
	s_add_i32 s77, 0, 0x18000
	s_add_i32 s78, 0, 0x1c000
	v_add_u32_e32 v126, s77, v159
	v_add_u32_e32 v154, s78, v159
	ds_read_b128 v[114:117], v126
	ds_read_b128 v[118:121], v126 offset:1024
	ds_read_b128 v[122:125], v126 offset:2048
	ds_read_b128 v[126:129], v126 offset:3072
	ds_read_b128 v[182:185], v154
	ds_read_b128 v[186:189], v154 offset:1024
	ds_read_b128 v[190:193], v154 offset:2048
	ds_read_b128 v[194:197], v154 offset:3072
	s_add_u32 s12, s12, 0x80000
	s_addc_u32 s13, s13, 0
	s_mov_b32 m0, s37
	v_lshl_add_u64 v[236:237], s[12:13], 0, v[146:147]
	ds_read_b128 v[198:201], v179 offset:32768
	ds_read_b128 v[202:205], v179 offset:33792
	ds_read_b128 v[206:209], v179 offset:34816
	ds_read_b128 v[210:213], v179 offset:35840
	ds_read_b128 v[214:217], v179 offset:36864
	ds_read_b128 v[218:221], v179 offset:37888
	ds_read_b128 v[222:225], v179 offset:38912
	ds_read_b128 v[226:229], v179 offset:39936
	global_load_lds_dwordx4 v[236:237], off
	v_lshl_add_u64 v[236:237], s[12:13], 0, v[150:151]
	s_mov_b32 m0, s38
	s_nop 0
	global_load_lds_dwordx4 v[236:237], off
	s_waitcnt vmcnt(8)
	s_waitcnt lgkmcnt(0)
	s_barrier
	s_waitcnt lgkmcnt(0)
	v_mfma_f32_16x16x32_bf16 v[142:145], v[114:117], v[198:201], v[142:145]
	v_mfma_f32_16x16x32_bf16 v[138:141], v[122:125], v[198:201], v[138:141]
	v_mfma_f32_16x16x32_bf16 v[110:113], v[114:117], v[206:209], v[110:113]
	v_mfma_f32_16x16x32_bf16 v[106:109], v[122:125], v[206:209], v[106:109]
	v_mfma_f32_16x16x32_bf16 v[94:97], v[114:117], v[214:217], v[94:97]
	v_mfma_f32_16x16x32_bf16 v[90:93], v[122:125], v[214:217], v[90:93]
	v_mfma_f32_16x16x32_bf16 v[78:81], v[114:117], v[222:225], v[78:81]
	v_mfma_f32_16x16x32_bf16 v[74:77], v[122:125], v[222:225], v[74:77]
	v_mfma_f32_16x16x32_bf16 v[142:145], v[118:121], v[202:205], v[142:145]
	v_mfma_f32_16x16x32_bf16 v[138:141], v[126:129], v[202:205], v[138:141]
	v_mfma_f32_16x16x32_bf16 v[110:113], v[118:121], v[210:213], v[110:113]
	v_mfma_f32_16x16x32_bf16 v[106:109], v[126:129], v[210:213], v[106:109]
	v_mfma_f32_16x16x32_bf16 v[94:97], v[118:121], v[218:221], v[94:97]
	v_mfma_f32_16x16x32_bf16 v[90:93], v[126:129], v[218:221], v[90:93]
	v_mfma_f32_16x16x32_bf16 v[78:81], v[118:121], v[226:229], v[78:81]
	v_mfma_f32_16x16x32_bf16 v[74:77], v[126:129], v[226:229], v[74:77]
	v_mfma_f32_16x16x32_bf16 v[134:137], v[182:185], v[198:201], v[134:137]
	v_mfma_f32_16x16x32_bf16 v[130:133], v[190:193], v[198:201], v[130:133]
	v_mfma_f32_16x16x32_bf16 v[102:105], v[182:185], v[206:209], v[102:105]
	v_mfma_f32_16x16x32_bf16 v[98:101], v[190:193], v[206:209], v[98:101]
	v_mfma_f32_16x16x32_bf16 v[86:89], v[182:185], v[214:217], v[86:89]
	v_mfma_f32_16x16x32_bf16 v[82:85], v[190:193], v[214:217], v[82:85]
	v_mfma_f32_16x16x32_bf16 v[70:73], v[182:185], v[222:225], v[70:73]
	v_mfma_f32_16x16x32_bf16 v[66:69], v[190:193], v[222:225], v[66:69]
	v_mfma_f32_16x16x32_bf16 v[134:137], v[186:189], v[202:205], v[134:137]
	v_mfma_f32_16x16x32_bf16 v[130:133], v[194:197], v[202:205], v[130:133]
	v_mfma_f32_16x16x32_bf16 v[102:105], v[186:189], v[210:213], v[102:105]
	v_mfma_f32_16x16x32_bf16 v[98:101], v[194:197], v[210:213], v[98:101]
	v_mfma_f32_16x16x32_bf16 v[86:89], v[186:189], v[218:221], v[86:89]
	v_mfma_f32_16x16x32_bf16 v[82:85], v[194:197], v[218:221], v[82:85]
	v_mfma_f32_16x16x32_bf16 v[70:73], v[186:189], v[226:229], v[70:73]
	v_mfma_f32_16x16x32_bf16 v[66:69], v[194:197], v[226:229], v[66:69]
	s_barrier
	s_add_i32 s12, s77, s34
	v_lshl_add_u64 v[174:175], v[174:175], 0, s[52:53]
	s_mov_b32 m0, s12
	ds_read_b128 v[198:201], v179 offset:49152
	ds_read_b128 v[202:205], v179 offset:50176
	ds_read_b128 v[206:209], v179 offset:51200
	ds_read_b128 v[210:213], v179 offset:52224
	ds_read_b128 v[214:217], v179 offset:53248
	ds_read_b128 v[218:221], v179 offset:54272
	ds_read_b128 v[222:225], v179 offset:55296
	ds_read_b128 v[226:229], v179 offset:56320
	global_load_lds_dwordx4 v[174:175], off
	s_add_i32 m0, s12, 0x2000
	s_add_u32 s0, s0, 0x20080
	v_lshl_add_u64 v[174:175], v[230:231], 0, s[52:53]
	s_addc_u32 s1, s1, 0
	s_add_i32 s12, s78, s34
	global_load_lds_dwordx4 v[174:175], off
	v_lshl_add_u64 v[174:175], s[0:1], 0, v[148:149]
	s_mov_b32 m0, s12
	s_nop 0
	global_load_lds_dwordx4 v[174:175], off
	v_lshl_add_u64 v[174:175], s[0:1], 0, v[152:153]
	s_add_i32 m0, s12, 0x2000
	s_nop 0
	global_load_lds_dwordx4 v[174:175], off
	v_lshl_add_u64 v[174:175], v[232:233], 0, s[52:53]
	s_mov_b32 m0, s44
	s_nop 0
	global_load_lds_dwordx4 v[174:175], off
	v_lshl_add_u64 v[174:175], v[234:235], 0, s[52:53]
	s_mov_b32 m0, s45
	s_nop 0
	global_load_lds_dwordx4 v[174:175], off
	s_waitcnt vmcnt(8)
	s_waitcnt lgkmcnt(0)
	s_barrier
	s_waitcnt lgkmcnt(0)
	v_mfma_f32_16x16x32_bf16 v[62:65], v[114:117], v[198:201], v[62:65]
	v_mfma_f32_16x16x32_bf16 v[58:61], v[122:125], v[198:201], v[58:61]
	v_mfma_f32_16x16x32_bf16 v[46:49], v[114:117], v[206:209], v[46:49]
	v_mfma_f32_16x16x32_bf16 v[42:45], v[122:125], v[206:209], v[42:45]
	v_mfma_f32_16x16x32_bf16 v[30:33], v[114:117], v[214:217], v[30:33]
	v_mfma_f32_16x16x32_bf16 v[26:29], v[122:125], v[214:217], v[26:29]
	v_mfma_f32_16x16x32_bf16 v[14:17], v[114:117], v[222:225], v[14:17]
	v_mfma_f32_16x16x32_bf16 v[10:13], v[122:125], v[222:225], v[10:13]
	v_mfma_f32_16x16x32_bf16 v[62:65], v[118:121], v[202:205], v[62:65]
	v_mfma_f32_16x16x32_bf16 v[58:61], v[126:129], v[202:205], v[58:61]
	v_mfma_f32_16x16x32_bf16 v[46:49], v[118:121], v[210:213], v[46:49]
	v_mfma_f32_16x16x32_bf16 v[42:45], v[126:129], v[210:213], v[42:45]
	v_mfma_f32_16x16x32_bf16 v[30:33], v[118:121], v[218:221], v[30:33]
	v_mfma_f32_16x16x32_bf16 v[26:29], v[126:129], v[218:221], v[26:29]
	v_mfma_f32_16x16x32_bf16 v[14:17], v[118:121], v[226:229], v[14:17]
	v_mfma_f32_16x16x32_bf16 v[10:13], v[126:129], v[226:229], v[10:13]
	v_mfma_f32_16x16x32_bf16 v[54:57], v[182:185], v[198:201], v[54:57]
	v_mfma_f32_16x16x32_bf16 v[50:53], v[190:193], v[198:201], v[50:53]
	v_mfma_f32_16x16x32_bf16 v[38:41], v[182:185], v[206:209], v[38:41]
	v_mfma_f32_16x16x32_bf16 v[34:37], v[190:193], v[206:209], v[34:37]
	v_mfma_f32_16x16x32_bf16 v[22:25], v[182:185], v[214:217], v[22:25]
	v_mfma_f32_16x16x32_bf16 v[18:21], v[190:193], v[214:217], v[18:21]
	v_mfma_f32_16x16x32_bf16 v[6:9], v[182:185], v[222:225], v[6:9]
	v_mfma_f32_16x16x32_bf16 v[2:5], v[190:193], v[222:225], v[2:5]
	v_mfma_f32_16x16x32_bf16 v[54:57], v[186:189], v[202:205], v[54:57]
	v_mfma_f32_16x16x32_bf16 v[50:53], v[194:197], v[202:205], v[50:53]
	v_mfma_f32_16x16x32_bf16 v[38:41], v[186:189], v[210:213], v[38:41]
	v_mfma_f32_16x16x32_bf16 v[34:37], v[194:197], v[210:213], v[34:37]
	v_mfma_f32_16x16x32_bf16 v[22:25], v[186:189], v[218:221], v[22:25]
	v_mfma_f32_16x16x32_bf16 v[18:21], v[194:197], v[218:221], v[18:21]
	v_mfma_f32_16x16x32_bf16 v[6:9], v[186:189], v[226:229], v[6:9]
	v_mfma_f32_16x16x32_bf16 v[2:5], v[194:197], v[226:229], v[2:5]
	s_barrier
	s_add_i32 s76, s76, 2
	s_add_u32 s70, s70, 0x100
	s_addc_u32 s71, s71, 0
	s_add_u32 s20, s20, 0x100
	s_addc_u32 s21, s21, 0
	s_cmp_gt_u32 s76, 29
	s_cbranch_scc0 .LBB0_165
	s_and_b64 vcc, exec, s[56:57]
	s_cbranch_vccz .LBB0_168
	s_barrier

.LBB0_497:
	ds_read_b128 v[108:111], v215
	ds_read_b128 v[132:135], v215 offset:1024
	ds_read_b128 v[136:139], v215 offset:2048
	ds_read_b128 v[140:143], v215 offset:3072
	ds_read_b128 v[144:147], v220
	ds_read_b128 v[148:151], v220 offset:1024
	ds_read_b128 v[152:155], v220 offset:2048
	ds_read_b128 v[156:159], v220 offset:3072
	s_add_u32 s48, s8, 0xfff80080
	s_addc_u32 s49, s9, -1
	s_cmp_eq_u32 s65, 28
	s_cselect_b32 s51, s63, s49
	s_cselect_b32 s50, s64, s48
	s_cselect_b32 s49, s13, s47
	s_cselect_b32 s48, s12, s46
	v_lshl_add_u64 v[244:245], s[8:9], 0, v[178:179]
	s_add_i32 m0, s11, 0xc000
	ds_read_b128 v[184:187], v216
	ds_read_b128 v[188:191], v216 offset:1024
	ds_read_b128 v[192:195], v216 offset:2048
	ds_read_b128 v[224:227], v216 offset:3072
	ds_read_b128 v[228:231], v216 offset:4096
	ds_read_b128 v[232:235], v216 offset:5120
	ds_read_b128 v[236:239], v216 offset:6144
	ds_read_b128 v[240:243], v216 offset:7168
	global_load_lds_dwordx4 v[244:245], off
	v_lshl_add_u64 v[244:245], s[8:9], 0, v[180:181]
	s_add_i32 m0, s11, 0xe000
	s_nop 0
	global_load_lds_dwordx4 v[244:245], off
	s_waitcnt vmcnt(8)
	s_waitcnt lgkmcnt(0)
	s_barrier
	s_waitcnt lgkmcnt(0)
	v_mfma_f32_16x16x32_bf16 v[100:103], v[108:111], v[184:187], v[100:103]
	v_mfma_f32_16x16x32_bf16 v[96:99], v[136:139], v[184:187], v[96:99]
	v_mfma_f32_16x16x32_bf16 v[128:131], v[108:111], v[192:195], v[128:131]
	v_mfma_f32_16x16x32_bf16 v[76:79], v[136:139], v[192:195], v[76:79]
	v_mfma_f32_16x16x32_bf16 v[124:127], v[108:111], v[228:231], v[124:127]
	v_mfma_f32_16x16x32_bf16 v[120:123], v[136:139], v[228:231], v[120:123]
	v_mfma_f32_16x16x32_bf16 v[112:115], v[108:111], v[236:239], v[112:115]
	v_mfma_f32_16x16x32_bf16 v[116:119], v[136:139], v[236:239], v[116:119]
	v_mfma_f32_16x16x32_bf16 v[100:103], v[132:135], v[188:191], v[100:103]
	v_mfma_f32_16x16x32_bf16 v[96:99], v[140:143], v[188:191], v[96:99]
	v_mfma_f32_16x16x32_bf16 v[128:131], v[132:135], v[224:227], v[128:131]
	v_mfma_f32_16x16x32_bf16 v[76:79], v[140:143], v[224:227], v[76:79]
	v_mfma_f32_16x16x32_bf16 v[124:127], v[132:135], v[232:235], v[124:127]
	v_mfma_f32_16x16x32_bf16 v[120:123], v[140:143], v[232:235], v[120:123]
	v_mfma_f32_16x16x32_bf16 v[112:115], v[132:135], v[240:243], v[112:115]
	v_mfma_f32_16x16x32_bf16 v[116:119], v[140:143], v[240:243], v[116:119]
	v_mfma_f32_16x16x32_bf16 v[92:95], v[144:147], v[184:187], v[92:95]
	v_mfma_f32_16x16x32_bf16 v[72:75], v[152:155], v[184:187], v[72:75]
	v_mfma_f32_16x16x32_bf16 v[64:67], v[144:147], v[192:195], v[64:67]
	v_mfma_f32_16x16x32_bf16 v[68:71], v[152:155], v[192:195], v[68:71]
	v_mfma_f32_16x16x32_bf16 v[84:87], v[144:147], v[228:231], v[84:87]
	v_mfma_f32_16x16x32_bf16 v[104:107], v[152:155], v[228:231], v[104:107]
	v_mfma_f32_16x16x32_bf16 v[80:83], v[144:147], v[236:239], v[80:83]
	v_mfma_f32_16x16x32_bf16 v[88:91], v[152:155], v[236:239], v[88:91]
	v_mfma_f32_16x16x32_bf16 v[92:95], v[148:151], v[188:191], v[92:95]
	v_mfma_f32_16x16x32_bf16 v[72:75], v[156:159], v[188:191], v[72:75]
	v_mfma_f32_16x16x32_bf16 v[64:67], v[148:151], v[224:227], v[64:67]
	v_mfma_f32_16x16x32_bf16 v[68:71], v[156:159], v[224:227], v[68:71]
	v_mfma_f32_16x16x32_bf16 v[84:87], v[148:151], v[232:235], v[84:87]
	v_mfma_f32_16x16x32_bf16 v[104:107], v[156:159], v[232:235], v[104:107]
	v_mfma_f32_16x16x32_bf16 v[80:83], v[148:151], v[240:243], v[80:83]
	v_mfma_f32_16x16x32_bf16 v[88:91], v[156:159], v[240:243], v[88:91]
	s_barrier
	s_add_i32 s66, s29, s52
	v_lshl_add_u64 v[244:245], s[48:49], 0, v[162:163]
	s_mov_b32 m0, s66
	ds_read_b128 v[184:187], v216 offset:16384
	ds_read_b128 v[188:191], v216 offset:17408
	ds_read_b128 v[192:195], v216 offset:18432
	ds_read_b128 v[224:227], v216 offset:19456
	ds_read_b128 v[228:231], v216 offset:20480
	ds_read_b128 v[232:235], v216 offset:21504
	ds_read_b128 v[236:239], v216 offset:22528
	ds_read_b128 v[240:243], v216 offset:23552
	global_load_lds_dwordx4 v[244:245], off
	s_add_i32 m0, s66, 0x2000
	s_add_u32 s66, s48, 0x20000
	v_lshl_add_u64 v[246:247], s[48:49], 0, v[166:167]
	s_addc_u32 s67, s49, 0
	s_add_i32 s68, s59, s52
	global_load_lds_dwordx4 v[246:247], off
	v_lshl_add_u64 v[248:249], s[66:67], 0, v[162:163]
	s_mov_b32 m0, s68
	v_lshl_add_u64 v[250:251], s[50:51], 0, v[164:165]
	global_load_lds_dwordx4 v[248:249], off
	v_lshl_add_u64 v[248:249], s[66:67], 0, v[166:167]
	s_add_i32 m0, s68, 0x2000
	s_nop 0
	global_load_lds_dwordx4 v[248:249], off
	v_lshl_add_u64 v[248:249], s[50:51], 0, v[160:161]
	s_mov_b32 m0, s11
	s_nop 0
	global_load_lds_dwordx4 v[248:249], off
	s_mov_b32 m0, s33
	s_nop 0
	global_load_lds_dwordx4 v[250:251], off
	s_waitcnt vmcnt(8)
	s_waitcnt lgkmcnt(0)
	s_barrier
	s_waitcnt lgkmcnt(0)
	v_mfma_f32_16x16x32_bf16 v[12:15], v[108:111], v[184:187], v[12:15]
	v_mfma_f32_16x16x32_bf16 v[20:23], v[136:139], v[184:187], v[20:23]
	v_mfma_f32_16x16x32_bf16 v[24:27], v[108:111], v[192:195], v[24:27]
	v_mfma_f32_16x16x32_bf16 v[28:31], v[136:139], v[192:195], v[28:31]
	v_mfma_f32_16x16x32_bf16 v[40:43], v[108:111], v[228:231], v[40:43]
	v_mfma_f32_16x16x32_bf16 v[44:47], v[136:139], v[228:231], v[44:47]
	v_mfma_f32_16x16x32_bf16 v[48:51], v[108:111], v[236:239], v[48:51]
	v_mfma_f32_16x16x32_bf16 v[52:55], v[136:139], v[236:239], v[52:55]
	v_mfma_f32_16x16x32_bf16 v[12:15], v[132:135], v[188:191], v[12:15]
	v_mfma_f32_16x16x32_bf16 v[20:23], v[140:143], v[188:191], v[20:23]
	v_mfma_f32_16x16x32_bf16 v[24:27], v[132:135], v[224:227], v[24:27]
	v_mfma_f32_16x16x32_bf16 v[28:31], v[140:143], v[224:227], v[28:31]
	v_mfma_f32_16x16x32_bf16 v[40:43], v[132:135], v[232:235], v[40:43]
	v_mfma_f32_16x16x32_bf16 v[44:47], v[140:143], v[232:235], v[44:47]
	v_mfma_f32_16x16x32_bf16 v[48:51], v[132:135], v[240:243], v[48:51]
	v_mfma_f32_16x16x32_bf16 v[52:55], v[140:143], v[240:243], v[52:55]
	v_mfma_f32_16x16x32_bf16 v[0:3], v[144:147], v[184:187], v[0:3]
	v_mfma_f32_16x16x32_bf16 v[4:7], v[152:155], v[184:187], v[4:7]
	v_mfma_f32_16x16x32_bf16 v[8:11], v[144:147], v[192:195], v[8:11]
	v_mfma_f32_16x16x32_bf16 v[16:19], v[152:155], v[192:195], v[16:19]
	v_mfma_f32_16x16x32_bf16 v[32:35], v[144:147], v[228:231], v[32:35]
	v_mfma_f32_16x16x32_bf16 v[36:39], v[152:155], v[228:231], v[36:39]
	v_mfma_f32_16x16x32_bf16 v[56:59], v[144:147], v[236:239], v[56:59]
	v_mfma_f32_16x16x32_bf16 v[60:63], v[152:155], v[236:239], v[60:63]
	v_mfma_f32_16x16x32_bf16 v[0:3], v[148:151], v[188:191], v[0:3]
	v_mfma_f32_16x16x32_bf16 v[4:7], v[156:159], v[188:191], v[4:7]
	v_mfma_f32_16x16x32_bf16 v[8:11], v[148:151], v[224:227], v[8:11]
	v_mfma_f32_16x16x32_bf16 v[16:19], v[156:159], v[224:227], v[16:19]
	v_mfma_f32_16x16x32_bf16 v[32:35], v[148:151], v[232:235], v[32:35]
	v_mfma_f32_16x16x32_bf16 v[36:39], v[156:159], v[232:235], v[36:39]
	v_mfma_f32_16x16x32_bf16 v[56:59], v[148:151], v[240:243], v[56:59]
	v_mfma_f32_16x16x32_bf16 v[60:63], v[156:159], v[240:243], v[60:63]
	s_barrier
	s_add_i32 s66, 0, 0x18000
	s_add_i32 s67, 0, 0x1c000
	v_add_u32_e32 v140, s66, v197
	v_add_u32_e32 v156, s67, v197
	ds_read_b128 v[108:111], v140
	ds_read_b128 v[132:135], v140 offset:1024
	ds_read_b128 v[136:139], v140 offset:2048
	ds_read_b128 v[140:143], v140 offset:3072
	ds_read_b128 v[144:147], v156
	ds_read_b128 v[148:151], v156 offset:1024
	ds_read_b128 v[152:155], v156 offset:2048
	ds_read_b128 v[156:159], v156 offset:3072
	s_add_u32 s50, s50, 0x80000
	s_addc_u32 s51, s51, 0
	s_mov_b32 m0, s53
	v_lshl_add_u64 v[252:253], s[50:51], 0, v[160:161]
	ds_read_b128 v[184:187], v216 offset:32768
	ds_read_b128 v[188:191], v216 offset:33792
	ds_read_b128 v[192:195], v216 offset:34816
	ds_read_b128 v[224:227], v216 offset:35840
	ds_read_b128 v[228:231], v216 offset:36864
	ds_read_b128 v[232:235], v216 offset:37888
	ds_read_b128 v[236:239], v216 offset:38912
	ds_read_b128 v[240:243], v216 offset:39936
	global_load_lds_dwordx4 v[252:253], off
	v_lshl_add_u64 v[252:253], s[50:51], 0, v[164:165]
	s_mov_b32 m0, s54
	s_nop 0
	global_load_lds_dwordx4 v[252:253], off
	s_waitcnt vmcnt(8)
	s_waitcnt lgkmcnt(0)
	s_barrier
	s_waitcnt lgkmcnt(0)
	v_mfma_f32_16x16x32_bf16 v[100:103], v[108:111], v[184:187], v[100:103]
	v_mfma_f32_16x16x32_bf16 v[96:99], v[136:139], v[184:187], v[96:99]
	v_mfma_f32_16x16x32_bf16 v[128:131], v[108:111], v[192:195], v[128:131]
	v_mfma_f32_16x16x32_bf16 v[76:79], v[136:139], v[192:195], v[76:79]
	v_mfma_f32_16x16x32_bf16 v[124:127], v[108:111], v[228:231], v[124:127]
	v_mfma_f32_16x16x32_bf16 v[120:123], v[136:139], v[228:231], v[120:123]
	v_mfma_f32_16x16x32_bf16 v[112:115], v[108:111], v[236:239], v[112:115]
	v_mfma_f32_16x16x32_bf16 v[116:119], v[136:139], v[236:239], v[116:119]
	v_mfma_f32_16x16x32_bf16 v[100:103], v[132:135], v[188:191], v[100:103]
	v_mfma_f32_16x16x32_bf16 v[96:99], v[140:143], v[188:191], v[96:99]
	v_mfma_f32_16x16x32_bf16 v[128:131], v[132:135], v[224:227], v[128:131]
	v_mfma_f32_16x16x32_bf16 v[76:79], v[140:143], v[224:227], v[76:79]
	v_mfma_f32_16x16x32_bf16 v[124:127], v[132:135], v[232:235], v[124:127]
	v_mfma_f32_16x16x32_bf16 v[120:123], v[140:143], v[232:235], v[120:123]
	v_mfma_f32_16x16x32_bf16 v[112:115], v[132:135], v[240:243], v[112:115]
	v_mfma_f32_16x16x32_bf16 v[116:119], v[140:143], v[240:243], v[116:119]
	v_mfma_f32_16x16x32_bf16 v[92:95], v[144:147], v[184:187], v[92:95]
	v_mfma_f32_16x16x32_bf16 v[72:75], v[152:155], v[184:187], v[72:75]
	v_mfma_f32_16x16x32_bf16 v[64:67], v[144:147], v[192:195], v[64:67]
	v_mfma_f32_16x16x32_bf16 v[68:71], v[152:155], v[192:195], v[68:71]
	v_mfma_f32_16x16x32_bf16 v[84:87], v[144:147], v[228:231], v[84:87]
	v_mfma_f32_16x16x32_bf16 v[104:107], v[152:155], v[228:231], v[104:107]
	v_mfma_f32_16x16x32_bf16 v[80:83], v[144:147], v[236:239], v[80:83]
	v_mfma_f32_16x16x32_bf16 v[88:91], v[152:155], v[236:239], v[88:91]
	v_mfma_f32_16x16x32_bf16 v[92:95], v[148:151], v[188:191], v[92:95]
	v_mfma_f32_16x16x32_bf16 v[72:75], v[156:159], v[188:191], v[72:75]
	v_mfma_f32_16x16x32_bf16 v[64:67], v[148:151], v[224:227], v[64:67]
	v_mfma_f32_16x16x32_bf16 v[68:71], v[156:159], v[224:227], v[68:71]
	v_mfma_f32_16x16x32_bf16 v[84:87], v[148:151], v[232:235], v[84:87]
	v_mfma_f32_16x16x32_bf16 v[104:107], v[156:159], v[232:235], v[104:107]
	v_mfma_f32_16x16x32_bf16 v[80:83], v[148:151], v[240:243], v[80:83]
	v_mfma_f32_16x16x32_bf16 v[88:91], v[156:159], v[240:243], v[88:91]
	s_barrier
	s_add_i32 s50, s66, s52
	v_lshl_add_u64 v[244:245], v[244:245], 0, s[24:25]
	s_mov_b32 m0, s50
	ds_read_b128 v[184:187], v216 offset:49152
	ds_read_b128 v[188:191], v216 offset:50176
	ds_read_b128 v[192:195], v216 offset:51200
	ds_read_b128 v[224:227], v216 offset:52224
	ds_read_b128 v[228:231], v216 offset:53248
	ds_read_b128 v[232:235], v216 offset:54272
	ds_read_b128 v[236:239], v216 offset:55296
	ds_read_b128 v[240:243], v216 offset:56320
	global_load_lds_dwordx4 v[244:245], off
	s_add_i32 m0, s50, 0x2000
	s_add_u32 s48, s48, 0x20080
	v_lshl_add_u64 v[244:245], v[246:247], 0, s[24:25]
	s_addc_u32 s49, s49, 0
	s_add_i32 s50, s67, s52
	global_load_lds_dwordx4 v[244:245], off
	v_lshl_add_u64 v[244:245], s[48:49], 0, v[162:163]
	s_mov_b32 m0, s50
	s_nop 0
	global_load_lds_dwordx4 v[244:245], off
	v_lshl_add_u64 v[244:245], s[48:49], 0, v[166:167]
	s_add_i32 m0, s50, 0x2000
	s_nop 0
	global_load_lds_dwordx4 v[244:245], off
	v_lshl_add_u64 v[244:245], v[248:249], 0, s[24:25]
	s_mov_b32 m0, s57
	s_nop 0
	global_load_lds_dwordx4 v[244:245], off
	v_lshl_add_u64 v[244:245], v[250:251], 0, s[24:25]
	s_mov_b32 m0, s58
	s_nop 0
	global_load_lds_dwordx4 v[244:245], off
	s_waitcnt vmcnt(8)
	s_waitcnt lgkmcnt(0)
	s_barrier
	s_waitcnt lgkmcnt(0)
	v_mfma_f32_16x16x32_bf16 v[12:15], v[108:111], v[184:187], v[12:15]
	v_mfma_f32_16x16x32_bf16 v[20:23], v[136:139], v[184:187], v[20:23]
	v_mfma_f32_16x16x32_bf16 v[24:27], v[108:111], v[192:195], v[24:27]
	v_mfma_f32_16x16x32_bf16 v[28:31], v[136:139], v[192:195], v[28:31]
	v_mfma_f32_16x16x32_bf16 v[40:43], v[108:111], v[228:231], v[40:43]
	v_mfma_f32_16x16x32_bf16 v[44:47], v[136:139], v[228:231], v[44:47]
	v_mfma_f32_16x16x32_bf16 v[48:51], v[108:111], v[236:239], v[48:51]
	v_mfma_f32_16x16x32_bf16 v[52:55], v[136:139], v[236:239], v[52:55]
	v_mfma_f32_16x16x32_bf16 v[12:15], v[132:135], v[188:191], v[12:15]
	v_mfma_f32_16x16x32_bf16 v[20:23], v[140:143], v[188:191], v[20:23]
	v_mfma_f32_16x16x32_bf16 v[24:27], v[132:135], v[224:227], v[24:27]
	v_mfma_f32_16x16x32_bf16 v[28:31], v[140:143], v[224:227], v[28:31]
	v_mfma_f32_16x16x32_bf16 v[40:43], v[132:135], v[232:235], v[40:43]
	v_mfma_f32_16x16x32_bf16 v[44:47], v[140:143], v[232:235], v[44:47]
	v_mfma_f32_16x16x32_bf16 v[48:51], v[132:135], v[240:243], v[48:51]
	v_mfma_f32_16x16x32_bf16 v[52:55], v[140:143], v[240:243], v[52:55]
	v_mfma_f32_16x16x32_bf16 v[0:3], v[144:147], v[184:187], v[0:3]
	v_mfma_f32_16x16x32_bf16 v[4:7], v[152:155], v[184:187], v[4:7]
	v_mfma_f32_16x16x32_bf16 v[8:11], v[144:147], v[192:195], v[8:11]
	v_mfma_f32_16x16x32_bf16 v[16:19], v[152:155], v[192:195], v[16:19]
	v_mfma_f32_16x16x32_bf16 v[32:35], v[144:147], v[228:231], v[32:35]
	v_mfma_f32_16x16x32_bf16 v[36:39], v[152:155], v[228:231], v[36:39]
	v_mfma_f32_16x16x32_bf16 v[56:59], v[144:147], v[236:239], v[56:59]
	v_mfma_f32_16x16x32_bf16 v[60:63], v[152:155], v[236:239], v[60:63]
	v_mfma_f32_16x16x32_bf16 v[0:3], v[148:151], v[188:191], v[0:3]
	v_mfma_f32_16x16x32_bf16 v[4:7], v[156:159], v[188:191], v[4:7]
	v_mfma_f32_16x16x32_bf16 v[8:11], v[148:151], v[224:227], v[8:11]
	v_mfma_f32_16x16x32_bf16 v[16:19], v[156:159], v[224:227], v[16:19]
	v_mfma_f32_16x16x32_bf16 v[32:35], v[148:151], v[232:235], v[32:35]
	v_mfma_f32_16x16x32_bf16 v[36:39], v[156:159], v[232:235], v[36:39]
	v_mfma_f32_16x16x32_bf16 v[56:59], v[148:151], v[240:243], v[56:59]
	v_mfma_f32_16x16x32_bf16 v[60:63], v[156:159], v[240:243], v[60:63]
	s_barrier
	s_add_i32 s65, s65, 2
	s_add_u32 s8, s8, 0x100
	s_addc_u32 s9, s9, 0
	s_add_u32 s46, s46, 0x100
	s_addc_u32 s47, s47, 0
	s_cmp_gt_u32 s65, 29
	s_cbranch_scc0 .LBB0_497
	s_and_b64 vcc, exec, s[36:37]
	s_cbranch_vccz .LBB0_500
	s_barrier
